# f32-residual GEMM epilogues: base loads software-pipelined 13 deep with counted vmcnt instead of one vmcnt(0) round trip per 16B
# baseline (speedup 1.0000x reference)
.LBB0_679:
	v_lshl_add_u32 v158, s36, 8, v146
	v_lshl_or_b32 v160, s67, 8, v148
	v_ashrrev_i32_e32 v159, 31, v158
	v_ashrrev_i32_e32 v161, 31, v160
	v_lshlrev_b64 v[144:145], 10, v[158:159]
	v_lshl_add_u64 v[144:145], v[144:145], 0, v[160:161]
	v_lshlrev_b64 v[144:145], 2, v[144:145]
	v_lshl_add_u64 v[162:163], s[6:7], 0, v[144:145]
	v_lshl_add_u64 v[164:165], s[10:11], 0, v[144:145]
	s_mov_b32 s99, 0
	global_load_dwordx4 v[166:169], v[162:163], off
	global_load_dwordx4 v[170:173], v[162:163], off offset:64
	global_load_dwordx4 v[174:177], v[162:163], off offset:512
	global_load_dwordx4 v[178:181], v[162:163], off offset:576
	s_mov_b32 s98, 0x10000
	v_lshl_add_u64 v[162:163], v[162:163], 0, s[98:99]
	global_load_dwordx4 v[182:185], v[162:163], off
	global_load_dwordx4 v[186:189], v[162:163], off offset:64
	global_load_dwordx4 v[190:193], v[162:163], off offset:512
	global_load_dwordx4 v[194:197], v[162:163], off offset:576
	s_mov_b32 s98, 0x10000
	v_lshl_add_u64 v[162:163], v[162:163], 0, s[98:99]
	global_load_dwordx4 v[198:201], v[162:163], off
	global_load_dwordx4 v[202:205], v[162:163], off offset:64
	global_load_dwordx4 v[206:209], v[162:163], off offset:512
	global_load_dwordx4 v[210:213], v[162:163], off offset:576
	s_mov_b32 s98, 0x10000
	v_lshl_add_u64 v[162:163], v[162:163], 0, s[98:99]
	global_load_dwordx4 v[214:217], v[162:163], off
	s_waitcnt vmcnt(12)
	v_pk_add_f32 v[126:127], v[126:127], v[168:169]
	v_pk_add_f32 v[124:125], v[124:125], v[166:167]
	global_store_dwordx4 v[164:165], v[124:127], off
	global_load_dwordx4 v[166:169], v[162:163], off offset:64
	s_waitcnt vmcnt(13)
	v_pk_add_f32 v[122:123], v[122:123], v[172:173]
	v_pk_add_f32 v[120:121], v[120:121], v[170:171]
	global_store_dwordx4 v[164:165], v[120:123], off offset:64
	global_load_dwordx4 v[170:173], v[162:163], off offset:512
	s_waitcnt vmcnt(14)
	v_pk_add_f32 v[118:119], v[118:119], v[176:177]
	v_pk_add_f32 v[116:117], v[116:117], v[174:175]
	global_store_dwordx4 v[164:165], v[116:119], off offset:512
	global_load_dwordx4 v[174:177], v[162:163], off offset:576
	s_waitcnt vmcnt(15)
	v_pk_add_f32 v[106:107], v[106:107], v[180:181]
	v_pk_add_f32 v[104:105], v[104:105], v[178:179]
	global_store_dwordx4 v[164:165], v[104:107], off offset:576
	s_mov_b32 s98, 0x50000
	v_lshl_add_u64 v[162:163], v[162:163], 0, s[98:99]
	global_load_dwordx4 v[178:181], v[162:163], off
	s_waitcnt vmcnt(16)
	s_mov_b32 s98, 0x10000
	v_lshl_add_u64 v[164:165], v[164:165], 0, s[98:99]
	v_pk_add_f32 v[114:115], v[114:115], v[184:185]
	v_pk_add_f32 v[112:113], v[112:113], v[182:183]
	global_store_dwordx4 v[164:165], v[112:115], off
	global_load_dwordx4 v[182:185], v[162:163], off offset:64
	s_waitcnt vmcnt(17)
	v_pk_add_f32 v[110:111], v[110:111], v[188:189]
	v_pk_add_f32 v[108:109], v[108:109], v[186:187]
	global_store_dwordx4 v[164:165], v[108:111], off offset:64
	global_load_dwordx4 v[186:189], v[162:163], off offset:512
	s_waitcnt vmcnt(18)
	v_pk_add_f32 v[102:103], v[102:103], v[192:193]
	v_pk_add_f32 v[100:101], v[100:101], v[190:191]
	global_store_dwordx4 v[164:165], v[100:103], off offset:512
	global_load_dwordx4 v[190:193], v[162:163], off offset:576
	s_waitcnt vmcnt(19)
	v_pk_add_f32 v[90:91], v[90:91], v[196:197]
	v_pk_add_f32 v[88:89], v[88:89], v[194:195]
	global_store_dwordx4 v[164:165], v[88:91], off offset:576
	s_mov_b32 s98, 0x10000
	v_lshl_add_u64 v[162:163], v[162:163], 0, s[98:99]
	global_load_dwordx4 v[194:197], v[162:163], off
	s_waitcnt vmcnt(20)
	s_mov_b32 s98, 0x10000
	v_lshl_add_u64 v[164:165], v[164:165], 0, s[98:99]
	v_pk_add_f32 v[98:99], v[98:99], v[200:201]
	v_pk_add_f32 v[96:97], v[96:97], v[198:199]
	global_store_dwordx4 v[164:165], v[96:99], off
	global_load_dwordx4 v[198:201], v[162:163], off offset:64
	s_waitcnt vmcnt(21)
	v_pk_add_f32 v[94:95], v[94:95], v[204:205]
	v_pk_add_f32 v[92:93], v[92:93], v[202:203]
	global_store_dwordx4 v[164:165], v[92:95], off offset:64
	global_load_dwordx4 v[202:205], v[162:163], off offset:512
	s_waitcnt vmcnt(22)
	v_pk_add_f32 v[86:87], v[86:87], v[208:209]
	v_pk_add_f32 v[84:85], v[84:85], v[206:207]
	global_store_dwordx4 v[164:165], v[84:87], off offset:512
	global_load_dwordx4 v[206:209], v[162:163], off offset:576
	s_waitcnt vmcnt(23)
	v_pk_add_f32 v[74:75], v[74:75], v[212:213]
	v_pk_add_f32 v[72:73], v[72:73], v[210:211]
	global_store_dwordx4 v[164:165], v[72:75], off offset:576
	s_mov_b32 s98, 0x10000
	v_lshl_add_u64 v[162:163], v[162:163], 0, s[98:99]
	global_load_dwordx4 v[210:213], v[162:163], off
	s_waitcnt vmcnt(24)
	s_mov_b32 s98, 0x10000
	v_lshl_add_u64 v[164:165], v[164:165], 0, s[98:99]
	v_pk_add_f32 v[82:83], v[82:83], v[216:217]
	v_pk_add_f32 v[80:81], v[80:81], v[214:215]
	global_store_dwordx4 v[164:165], v[80:83], off
	global_load_dwordx4 v[214:217], v[162:163], off offset:64
	s_waitcnt vmcnt(24)
	v_pk_add_f32 v[78:79], v[78:79], v[168:169]
	v_pk_add_f32 v[76:77], v[76:77], v[166:167]
	global_store_dwordx4 v[164:165], v[76:79], off offset:64
	global_load_dwordx4 v[166:169], v[162:163], off offset:512
	s_waitcnt vmcnt(24)
	v_pk_add_f32 v[70:71], v[70:71], v[172:173]
	v_pk_add_f32 v[68:69], v[68:69], v[170:171]
	global_store_dwordx4 v[164:165], v[68:71], off offset:512
	global_load_dwordx4 v[170:173], v[162:163], off offset:576
	s_waitcnt vmcnt(24)
	v_pk_add_f32 v[66:67], v[66:67], v[176:177]
	v_pk_add_f32 v[64:65], v[64:65], v[174:175]
	global_store_dwordx4 v[164:165], v[64:67], off offset:576
	s_mov_b32 s98, 0x10000
	v_lshl_add_u64 v[162:163], v[162:163], 0, s[98:99]
	global_load_dwordx4 v[174:177], v[162:163], off
	s_waitcnt vmcnt(24)
	s_mov_b32 s98, 0x50000
	v_lshl_add_u64 v[164:165], v[164:165], 0, s[98:99]
	v_pk_add_f32 v[62:63], v[62:63], v[180:181]
	v_pk_add_f32 v[60:61], v[60:61], v[178:179]
	global_store_dwordx4 v[164:165], v[60:63], off
	global_load_dwordx4 v[178:181], v[162:163], off offset:64
	s_waitcnt vmcnt(24)
	v_pk_add_f32 v[58:59], v[58:59], v[184:185]
	v_pk_add_f32 v[56:57], v[56:57], v[182:183]
	global_store_dwordx4 v[164:165], v[56:59], off offset:64
	global_load_dwordx4 v[182:185], v[162:163], off offset:512
	s_waitcnt vmcnt(24)
	v_pk_add_f32 v[54:55], v[54:55], v[188:189]
	v_pk_add_f32 v[52:53], v[52:53], v[186:187]
	global_store_dwordx4 v[164:165], v[52:55], off offset:512
	global_load_dwordx4 v[186:189], v[162:163], off offset:576
	s_waitcnt vmcnt(24)
	v_pk_add_f32 v[42:43], v[42:43], v[192:193]
	v_pk_add_f32 v[40:41], v[40:41], v[190:191]
	global_store_dwordx4 v[164:165], v[40:43], off offset:576
	s_waitcnt vmcnt(23)
	s_mov_b32 s98, 0x10000
	v_lshl_add_u64 v[164:165], v[164:165], 0, s[98:99]
	v_pk_add_f32 v[50:51], v[50:51], v[196:197]
	v_pk_add_f32 v[48:49], v[48:49], v[194:195]
	global_store_dwordx4 v[164:165], v[48:51], off
	s_waitcnt vmcnt(22)
	v_pk_add_f32 v[46:47], v[46:47], v[200:201]
	v_pk_add_f32 v[44:45], v[44:45], v[198:199]
	global_store_dwordx4 v[164:165], v[44:47], off offset:64
	s_waitcnt vmcnt(21)
	v_pk_add_f32 v[38:39], v[38:39], v[204:205]
	v_pk_add_f32 v[36:37], v[36:37], v[202:203]
	global_store_dwordx4 v[164:165], v[36:39], off offset:512
	s_waitcnt vmcnt(20)
	v_pk_add_f32 v[26:27], v[26:27], v[208:209]
	v_pk_add_f32 v[24:25], v[24:25], v[206:207]
	global_store_dwordx4 v[164:165], v[24:27], off offset:576
	s_waitcnt vmcnt(19)
	s_mov_b32 s98, 0x10000
	v_lshl_add_u64 v[164:165], v[164:165], 0, s[98:99]
	v_pk_add_f32 v[34:35], v[34:35], v[212:213]
	v_pk_add_f32 v[32:33], v[32:33], v[210:211]
	global_store_dwordx4 v[164:165], v[32:35], off
	s_waitcnt vmcnt(18)
	v_pk_add_f32 v[30:31], v[30:31], v[216:217]
	v_pk_add_f32 v[28:29], v[28:29], v[214:215]
	global_store_dwordx4 v[164:165], v[28:31], off offset:64
	s_waitcnt vmcnt(17)
	v_pk_add_f32 v[22:23], v[22:23], v[168:169]
	v_pk_add_f32 v[20:21], v[20:21], v[166:167]
	global_store_dwordx4 v[164:165], v[20:23], off offset:512
	s_waitcnt vmcnt(16)
	v_pk_add_f32 v[10:11], v[10:11], v[172:173]
	v_pk_add_f32 v[8:9], v[8:9], v[170:171]
	global_store_dwordx4 v[164:165], v[8:11], off offset:576
	s_waitcnt vmcnt(15)
	s_mov_b32 s98, 0x10000
	v_lshl_add_u64 v[164:165], v[164:165], 0, s[98:99]
	v_pk_add_f32 v[18:19], v[18:19], v[176:177]
	v_pk_add_f32 v[16:17], v[16:17], v[174:175]
	global_store_dwordx4 v[164:165], v[16:19], off
	s_waitcnt vmcnt(14)
	v_pk_add_f32 v[14:15], v[14:15], v[180:181]
	v_pk_add_f32 v[12:13], v[12:13], v[178:179]
	global_store_dwordx4 v[164:165], v[12:15], off offset:64
	s_waitcnt vmcnt(13)
	v_pk_add_f32 v[6:7], v[6:7], v[184:185]
	v_pk_add_f32 v[4:5], v[4:5], v[182:183]
	global_store_dwordx4 v[164:165], v[4:7], off offset:512
	s_waitcnt vmcnt(12)
	v_pk_add_f32 v[2:3], v[2:3], v[188:189]
	v_pk_add_f32 v[0:1], v[0:1], v[186:187]
	global_store_dwordx4 v[164:165], v[0:3], off offset:576
	s_andn2_b64 vcc, exec, s[4:5]
	s_mov_b64 s[4:5], -1
	s_cbranch_vccnz .LBB0_668
	s_andn2_b64 vcc, exec, s[8:9]
	s_cbranch_vccnz .LBB0_667
	s_barrier
	s_branch .LBB0_667

.LBB0_873:
	v_lshl_add_u32 v148, s66, 8, v150
	v_lshl_or_b32 v144, s67, 8, v154
	v_ashrrev_i32_e32 v149, 31, v148
	v_ashrrev_i32_e32 v145, 31, v144
	v_lshlrev_b64 v[146:147], 12, v[148:149]
	v_lshl_add_u64 v[158:159], s[14:15], 0, v[146:147]
	v_lshlrev_b64 v[146:147], 2, v[144:145]
	v_lshl_add_u64 v[144:145], v[158:159], 0, v[146:147]
	v_mov_b32_e32 v158, v144
	v_mov_b32_e32 v159, v145
	s_mov_b32 s99, 0
	global_load_dwordx4 v[166:169], v[144:145], off
	global_load_dwordx4 v[170:173], v[144:145], off offset:64
	global_load_dwordx4 v[174:177], v[144:145], off offset:512
	global_load_dwordx4 v[178:181], v[144:145], off offset:576
	s_mov_b32 s98, 0x10000
	v_lshl_add_u64 v[144:145], v[144:145], 0, s[98:99]
	global_load_dwordx4 v[182:185], v[144:145], off
	global_load_dwordx4 v[186:189], v[144:145], off offset:64
	global_load_dwordx4 v[190:193], v[144:145], off offset:512
	global_load_dwordx4 v[194:197], v[144:145], off offset:576
	s_mov_b32 s98, 0x10000
	v_lshl_add_u64 v[144:145], v[144:145], 0, s[98:99]
	global_load_dwordx4 v[198:201], v[144:145], off
	global_load_dwordx4 v[202:205], v[144:145], off offset:64
	global_load_dwordx4 v[206:209], v[144:145], off offset:512
	global_load_dwordx4 v[210:213], v[144:145], off offset:576
	s_mov_b32 s98, 0x10000
	v_lshl_add_u64 v[144:145], v[144:145], 0, s[98:99]
	global_load_dwordx4 v[214:217], v[144:145], off
	s_waitcnt vmcnt(12)
	v_pk_add_f32 v[126:127], v[126:127], v[168:169]
	v_pk_add_f32 v[124:125], v[124:125], v[166:167]
	global_store_dwordx4 v[158:159], v[124:127], off
	global_load_dwordx4 v[166:169], v[144:145], off offset:64
	s_waitcnt vmcnt(13)
	v_pk_add_f32 v[122:123], v[122:123], v[172:173]
	v_pk_add_f32 v[120:121], v[120:121], v[170:171]
	global_store_dwordx4 v[158:159], v[120:123], off offset:64
	global_load_dwordx4 v[170:173], v[144:145], off offset:512
	s_waitcnt vmcnt(14)
	v_pk_add_f32 v[118:119], v[118:119], v[176:177]
	v_pk_add_f32 v[116:117], v[116:117], v[174:175]
	global_store_dwordx4 v[158:159], v[116:119], off offset:512
	global_load_dwordx4 v[174:177], v[144:145], off offset:576
	s_waitcnt vmcnt(15)
	v_pk_add_f32 v[110:111], v[110:111], v[180:181]
	v_pk_add_f32 v[108:109], v[108:109], v[178:179]
	global_store_dwordx4 v[158:159], v[108:111], off offset:576
	s_mov_b32 s98, 0x50000
	v_lshl_add_u64 v[144:145], v[144:145], 0, s[98:99]
	global_load_dwordx4 v[178:181], v[144:145], off
	s_waitcnt vmcnt(16)
	s_mov_b32 s98, 0x10000
	v_lshl_add_u64 v[158:159], v[158:159], 0, s[98:99]
	v_pk_add_f32 v[114:115], v[114:115], v[184:185]
	v_pk_add_f32 v[112:113], v[112:113], v[182:183]
	global_store_dwordx4 v[158:159], v[112:115], off
	global_load_dwordx4 v[182:185], v[144:145], off offset:64
	s_waitcnt vmcnt(17)
	v_pk_add_f32 v[106:107], v[106:107], v[188:189]
	v_pk_add_f32 v[104:105], v[104:105], v[186:187]
	global_store_dwordx4 v[158:159], v[104:107], off offset:64
	global_load_dwordx4 v[186:189], v[144:145], off offset:512
	s_waitcnt vmcnt(18)
	v_pk_add_f32 v[102:103], v[102:103], v[192:193]
	v_pk_add_f32 v[100:101], v[100:101], v[190:191]
	global_store_dwordx4 v[158:159], v[100:103], off offset:512
	global_load_dwordx4 v[190:193], v[144:145], off offset:576
	s_waitcnt vmcnt(19)
	v_pk_add_f32 v[98:99], v[98:99], v[196:197]
	v_pk_add_f32 v[96:97], v[96:97], v[194:195]
	global_store_dwordx4 v[158:159], v[96:99], off offset:576
	s_mov_b32 s98, 0x10000
	v_lshl_add_u64 v[144:145], v[144:145], 0, s[98:99]
	global_load_dwordx4 v[194:197], v[144:145], off
	s_waitcnt vmcnt(20)
	s_mov_b32 s98, 0x10000
	v_lshl_add_u64 v[158:159], v[158:159], 0, s[98:99]
	v_pk_add_f32 v[94:95], v[94:95], v[200:201]
	v_pk_add_f32 v[92:93], v[92:93], v[198:199]
	global_store_dwordx4 v[158:159], v[92:95], off
	global_load_dwordx4 v[198:201], v[144:145], off offset:64
	s_waitcnt vmcnt(21)
	v_pk_add_f32 v[90:91], v[90:91], v[204:205]
	v_pk_add_f32 v[88:89], v[88:89], v[202:203]
	global_store_dwordx4 v[158:159], v[88:91], off offset:64
	global_load_dwordx4 v[202:205], v[144:145], off offset:512
	s_waitcnt vmcnt(22)
	v_pk_add_f32 v[86:87], v[86:87], v[208:209]
	v_pk_add_f32 v[84:85], v[84:85], v[206:207]
	global_store_dwordx4 v[158:159], v[84:87], off offset:512
	global_load_dwordx4 v[206:209], v[144:145], off offset:576
	s_waitcnt vmcnt(23)
	v_pk_add_f32 v[82:83], v[82:83], v[212:213]
	v_pk_add_f32 v[80:81], v[80:81], v[210:211]
	global_store_dwordx4 v[158:159], v[80:83], off offset:576
	s_mov_b32 s98, 0x10000
	v_lshl_add_u64 v[144:145], v[144:145], 0, s[98:99]
	global_load_dwordx4 v[210:213], v[144:145], off
	s_waitcnt vmcnt(24)
	s_mov_b32 s98, 0x10000
	v_lshl_add_u64 v[158:159], v[158:159], 0, s[98:99]
	v_pk_add_f32 v[78:79], v[78:79], v[216:217]
	v_pk_add_f32 v[76:77], v[76:77], v[214:215]
	global_store_dwordx4 v[158:159], v[76:79], off
	global_load_dwordx4 v[214:217], v[144:145], off offset:64
	s_waitcnt vmcnt(24)
	v_pk_add_f32 v[74:75], v[74:75], v[168:169]
	v_pk_add_f32 v[72:73], v[72:73], v[166:167]
	global_store_dwordx4 v[158:159], v[72:75], off offset:64
	global_load_dwordx4 v[166:169], v[144:145], off offset:512
	s_waitcnt vmcnt(24)
	v_pk_add_f32 v[70:71], v[70:71], v[172:173]
	v_pk_add_f32 v[68:69], v[68:69], v[170:171]
	global_store_dwordx4 v[158:159], v[68:71], off offset:512
	global_load_dwordx4 v[170:173], v[144:145], off offset:576
	s_waitcnt vmcnt(24)
	v_pk_add_f32 v[66:67], v[66:67], v[176:177]
	v_pk_add_f32 v[64:65], v[64:65], v[174:175]
	global_store_dwordx4 v[158:159], v[64:67], off offset:576
	s_mov_b32 s98, 0x10000
	v_lshl_add_u64 v[144:145], v[144:145], 0, s[98:99]
	global_load_dwordx4 v[174:177], v[144:145], off
	s_waitcnt vmcnt(24)
	s_mov_b32 s98, 0x50000
	v_lshl_add_u64 v[158:159], v[158:159], 0, s[98:99]
	v_pk_add_f32 v[62:63], v[62:63], v[180:181]
	v_pk_add_f32 v[60:61], v[60:61], v[178:179]
	global_store_dwordx4 v[158:159], v[60:63], off
	global_load_dwordx4 v[178:181], v[144:145], off offset:64
	s_waitcnt vmcnt(24)
	v_pk_add_f32 v[58:59], v[58:59], v[184:185]
	v_pk_add_f32 v[56:57], v[56:57], v[182:183]
	global_store_dwordx4 v[158:159], v[56:59], off offset:64
	global_load_dwordx4 v[182:185], v[144:145], off offset:512
	s_waitcnt vmcnt(24)
	v_pk_add_f32 v[54:55], v[54:55], v[188:189]
	v_pk_add_f32 v[52:53], v[52:53], v[186:187]
	global_store_dwordx4 v[158:159], v[52:55], off offset:512
	global_load_dwordx4 v[186:189], v[144:145], off offset:576
	s_waitcnt vmcnt(24)
	v_pk_add_f32 v[50:51], v[50:51], v[192:193]
	v_pk_add_f32 v[48:49], v[48:49], v[190:191]
	global_store_dwordx4 v[158:159], v[48:51], off offset:576
	s_waitcnt vmcnt(23)
	s_mov_b32 s98, 0x10000
	v_lshl_add_u64 v[158:159], v[158:159], 0, s[98:99]
	v_pk_add_f32 v[46:47], v[46:47], v[196:197]
	v_pk_add_f32 v[44:45], v[44:45], v[194:195]
	global_store_dwordx4 v[158:159], v[44:47], off
	s_waitcnt vmcnt(22)
	v_pk_add_f32 v[42:43], v[42:43], v[200:201]
	v_pk_add_f32 v[40:41], v[40:41], v[198:199]
	global_store_dwordx4 v[158:159], v[40:43], off offset:64
	s_waitcnt vmcnt(21)
	v_pk_add_f32 v[38:39], v[38:39], v[204:205]
	v_pk_add_f32 v[36:37], v[36:37], v[202:203]
	global_store_dwordx4 v[158:159], v[36:39], off offset:512
	s_waitcnt vmcnt(20)
	v_pk_add_f32 v[34:35], v[34:35], v[208:209]
	v_pk_add_f32 v[32:33], v[32:33], v[206:207]
	global_store_dwordx4 v[158:159], v[32:35], off offset:576
	s_waitcnt vmcnt(19)
	s_mov_b32 s98, 0x10000
	v_lshl_add_u64 v[158:159], v[158:159], 0, s[98:99]
	v_pk_add_f32 v[30:31], v[30:31], v[212:213]
	v_pk_add_f32 v[28:29], v[28:29], v[210:211]
	global_store_dwordx4 v[158:159], v[28:31], off
	s_waitcnt vmcnt(18)
	v_pk_add_f32 v[26:27], v[26:27], v[216:217]
	v_pk_add_f32 v[24:25], v[24:25], v[214:215]
	global_store_dwordx4 v[158:159], v[24:27], off offset:64
	s_waitcnt vmcnt(17)
	v_pk_add_f32 v[22:23], v[22:23], v[168:169]
	v_pk_add_f32 v[20:21], v[20:21], v[166:167]
	global_store_dwordx4 v[158:159], v[20:23], off offset:512
	s_waitcnt vmcnt(16)
	v_pk_add_f32 v[18:19], v[18:19], v[172:173]
	v_pk_add_f32 v[16:17], v[16:17], v[170:171]
	global_store_dwordx4 v[158:159], v[16:19], off offset:576
	s_waitcnt vmcnt(15)
	s_mov_b32 s98, 0x10000
	v_lshl_add_u64 v[158:159], v[158:159], 0, s[98:99]
	v_pk_add_f32 v[14:15], v[14:15], v[176:177]
	v_pk_add_f32 v[12:13], v[12:13], v[174:175]
	global_store_dwordx4 v[158:159], v[12:15], off
	s_waitcnt vmcnt(14)
	v_pk_add_f32 v[10:11], v[10:11], v[180:181]
	v_pk_add_f32 v[8:9], v[8:9], v[178:179]
	global_store_dwordx4 v[158:159], v[8:11], off offset:64
	s_waitcnt vmcnt(13)
	v_pk_add_f32 v[6:7], v[6:7], v[184:185]
	v_pk_add_f32 v[4:5], v[4:5], v[182:183]
	global_store_dwordx4 v[158:159], v[4:7], off offset:512
	s_waitcnt vmcnt(12)
	v_pk_add_f32 v[2:3], v[2:3], v[188:189]
	v_pk_add_f32 v[0:1], v[0:1], v[186:187]
	global_store_dwordx4 v[158:159], v[0:3], off offset:576
	s_mov_b64 s[28:29], -1
	s_and_b64 vcc, exec, s[4:5]
	s_cbranch_vccnz .LBB0_858
	s_andn2_b64 vcc, exec, s[10:11]
	s_cbranch_vccnz .LBB0_857
	s_barrier
	s_branch .LBB0_857

.LBB0_1561:
	v_lshl_add_u32 v148, s34, 8, v150
	v_lshl_or_b32 v144, s35, 8, v154
	v_ashrrev_i32_e32 v149, 31, v148
	v_ashrrev_i32_e32 v145, 31, v144
	v_lshlrev_b64 v[146:147], 12, v[148:149]
	v_lshl_add_u64 v[158:159], s[8:9], 0, v[146:147]
	v_lshlrev_b64 v[146:147], 2, v[144:145]
	v_lshl_add_u64 v[144:145], v[158:159], 0, v[146:147]
	v_mov_b32_e32 v158, v144
	v_mov_b32_e32 v159, v145
	s_mov_b32 s99, 0
	global_load_dwordx4 v[166:169], v[144:145], off
	global_load_dwordx4 v[170:173], v[144:145], off offset:64
	global_load_dwordx4 v[174:177], v[144:145], off offset:512
	global_load_dwordx4 v[178:181], v[144:145], off offset:576
	s_mov_b32 s98, 0x10000
	v_lshl_add_u64 v[144:145], v[144:145], 0, s[98:99]
	global_load_dwordx4 v[182:185], v[144:145], off
	global_load_dwordx4 v[186:189], v[144:145], off offset:64
	global_load_dwordx4 v[190:193], v[144:145], off offset:512
	global_load_dwordx4 v[194:197], v[144:145], off offset:576
	s_mov_b32 s98, 0x10000
	v_lshl_add_u64 v[144:145], v[144:145], 0, s[98:99]
	global_load_dwordx4 v[198:201], v[144:145], off
	global_load_dwordx4 v[202:205], v[144:145], off offset:64
	global_load_dwordx4 v[206:209], v[144:145], off offset:512
	global_load_dwordx4 v[210:213], v[144:145], off offset:576
	s_mov_b32 s98, 0x10000
	v_lshl_add_u64 v[144:145], v[144:145], 0, s[98:99]
	global_load_dwordx4 v[214:217], v[144:145], off
	s_waitcnt vmcnt(12)
	v_pk_add_f32 v[126:127], v[126:127], v[168:169]
	v_pk_add_f32 v[124:125], v[124:125], v[166:167]
	global_store_dwordx4 v[158:159], v[124:127], off
	global_load_dwordx4 v[166:169], v[144:145], off offset:64
	s_waitcnt vmcnt(13)
	v_pk_add_f32 v[122:123], v[122:123], v[172:173]
	v_pk_add_f32 v[120:121], v[120:121], v[170:171]
	global_store_dwordx4 v[158:159], v[120:123], off offset:64
	global_load_dwordx4 v[170:173], v[144:145], off offset:512
	s_waitcnt vmcnt(14)
	v_pk_add_f32 v[118:119], v[118:119], v[176:177]
	v_pk_add_f32 v[116:117], v[116:117], v[174:175]
	global_store_dwordx4 v[158:159], v[116:119], off offset:512
	global_load_dwordx4 v[174:177], v[144:145], off offset:576
	s_waitcnt vmcnt(15)
	v_pk_add_f32 v[110:111], v[110:111], v[180:181]
	v_pk_add_f32 v[108:109], v[108:109], v[178:179]
	global_store_dwordx4 v[158:159], v[108:111], off offset:576
	s_mov_b32 s98, 0x50000
	v_lshl_add_u64 v[144:145], v[144:145], 0, s[98:99]
	global_load_dwordx4 v[178:181], v[144:145], off
	s_waitcnt vmcnt(16)
	s_mov_b32 s98, 0x10000
	v_lshl_add_u64 v[158:159], v[158:159], 0, s[98:99]
	v_pk_add_f32 v[114:115], v[114:115], v[184:185]
	v_pk_add_f32 v[112:113], v[112:113], v[182:183]
	global_store_dwordx4 v[158:159], v[112:115], off
	global_load_dwordx4 v[182:185], v[144:145], off offset:64
	s_waitcnt vmcnt(17)
	v_pk_add_f32 v[106:107], v[106:107], v[188:189]
	v_pk_add_f32 v[104:105], v[104:105], v[186:187]
	global_store_dwordx4 v[158:159], v[104:107], off offset:64
	global_load_dwordx4 v[186:189], v[144:145], off offset:512
	s_waitcnt vmcnt(18)
	v_pk_add_f32 v[102:103], v[102:103], v[192:193]
	v_pk_add_f32 v[100:101], v[100:101], v[190:191]
	global_store_dwordx4 v[158:159], v[100:103], off offset:512
	global_load_dwordx4 v[190:193], v[144:145], off offset:576
	s_waitcnt vmcnt(19)
	v_pk_add_f32 v[98:99], v[98:99], v[196:197]
	v_pk_add_f32 v[96:97], v[96:97], v[194:195]
	global_store_dwordx4 v[158:159], v[96:99], off offset:576
	s_mov_b32 s98, 0x10000
	v_lshl_add_u64 v[144:145], v[144:145], 0, s[98:99]
	global_load_dwordx4 v[194:197], v[144:145], off
	s_waitcnt vmcnt(20)
	s_mov_b32 s98, 0x10000
	v_lshl_add_u64 v[158:159], v[158:159], 0, s[98:99]
	v_pk_add_f32 v[94:95], v[94:95], v[200:201]
	v_pk_add_f32 v[92:93], v[92:93], v[198:199]
	global_store_dwordx4 v[158:159], v[92:95], off
	global_load_dwordx4 v[198:201], v[144:145], off offset:64
	s_waitcnt vmcnt(21)
	v_pk_add_f32 v[90:91], v[90:91], v[204:205]
	v_pk_add_f32 v[88:89], v[88:89], v[202:203]
	global_store_dwordx4 v[158:159], v[88:91], off offset:64
	global_load_dwordx4 v[202:205], v[144:145], off offset:512
	s_waitcnt vmcnt(22)
	v_pk_add_f32 v[86:87], v[86:87], v[208:209]
	v_pk_add_f32 v[84:85], v[84:85], v[206:207]
	global_store_dwordx4 v[158:159], v[84:87], off offset:512
	global_load_dwordx4 v[206:209], v[144:145], off offset:576
	s_waitcnt vmcnt(23)
	v_pk_add_f32 v[82:83], v[82:83], v[212:213]
	v_pk_add_f32 v[80:81], v[80:81], v[210:211]
	global_store_dwordx4 v[158:159], v[80:83], off offset:576
	s_mov_b32 s98, 0x10000
	v_lshl_add_u64 v[144:145], v[144:145], 0, s[98:99]
	global_load_dwordx4 v[210:213], v[144:145], off
	s_waitcnt vmcnt(24)
	s_mov_b32 s98, 0x10000
	v_lshl_add_u64 v[158:159], v[158:159], 0, s[98:99]
	v_pk_add_f32 v[78:79], v[78:79], v[216:217]
	v_pk_add_f32 v[76:77], v[76:77], v[214:215]
	global_store_dwordx4 v[158:159], v[76:79], off
	global_load_dwordx4 v[214:217], v[144:145], off offset:64
	s_waitcnt vmcnt(24)
	v_pk_add_f32 v[74:75], v[74:75], v[168:169]
	v_pk_add_f32 v[72:73], v[72:73], v[166:167]
	global_store_dwordx4 v[158:159], v[72:75], off offset:64
	global_load_dwordx4 v[166:169], v[144:145], off offset:512
	s_waitcnt vmcnt(24)
	v_pk_add_f32 v[70:71], v[70:71], v[172:173]
	v_pk_add_f32 v[68:69], v[68:69], v[170:171]
	global_store_dwordx4 v[158:159], v[68:71], off offset:512
	global_load_dwordx4 v[170:173], v[144:145], off offset:576
	s_waitcnt vmcnt(24)
	v_pk_add_f32 v[66:67], v[66:67], v[176:177]
	v_pk_add_f32 v[64:65], v[64:65], v[174:175]
	global_store_dwordx4 v[158:159], v[64:67], off offset:576
	s_mov_b32 s98, 0x10000
	v_lshl_add_u64 v[144:145], v[144:145], 0, s[98:99]
	global_load_dwordx4 v[174:177], v[144:145], off
	s_waitcnt vmcnt(24)
	s_mov_b32 s98, 0x50000
	v_lshl_add_u64 v[158:159], v[158:159], 0, s[98:99]
	v_pk_add_f32 v[62:63], v[62:63], v[180:181]
	v_pk_add_f32 v[60:61], v[60:61], v[178:179]
	global_store_dwordx4 v[158:159], v[60:63], off
	global_load_dwordx4 v[178:181], v[144:145], off offset:64
	s_waitcnt vmcnt(24)
	v_pk_add_f32 v[58:59], v[58:59], v[184:185]
	v_pk_add_f32 v[56:57], v[56:57], v[182:183]
	global_store_dwordx4 v[158:159], v[56:59], off offset:64
	global_load_dwordx4 v[182:185], v[144:145], off offset:512
	s_waitcnt vmcnt(24)
	v_pk_add_f32 v[54:55], v[54:55], v[188:189]
	v_pk_add_f32 v[52:53], v[52:53], v[186:187]
	global_store_dwordx4 v[158:159], v[52:55], off offset:512
	global_load_dwordx4 v[186:189], v[144:145], off offset:576
	s_waitcnt vmcnt(24)
	v_pk_add_f32 v[50:51], v[50:51], v[192:193]
	v_pk_add_f32 v[48:49], v[48:49], v[190:191]
	global_store_dwordx4 v[158:159], v[48:51], off offset:576
	s_waitcnt vmcnt(23)
	s_mov_b32 s98, 0x10000
	v_lshl_add_u64 v[158:159], v[158:159], 0, s[98:99]
	v_pk_add_f32 v[46:47], v[46:47], v[196:197]
	v_pk_add_f32 v[44:45], v[44:45], v[194:195]
	global_store_dwordx4 v[158:159], v[44:47], off
	s_waitcnt vmcnt(22)
	v_pk_add_f32 v[42:43], v[42:43], v[200:201]
	v_pk_add_f32 v[40:41], v[40:41], v[198:199]
	global_store_dwordx4 v[158:159], v[40:43], off offset:64
	s_waitcnt vmcnt(21)
	v_pk_add_f32 v[38:39], v[38:39], v[204:205]
	v_pk_add_f32 v[36:37], v[36:37], v[202:203]
	global_store_dwordx4 v[158:159], v[36:39], off offset:512
	s_waitcnt vmcnt(20)
	v_pk_add_f32 v[34:35], v[34:35], v[208:209]
	v_pk_add_f32 v[32:33], v[32:33], v[206:207]
	global_store_dwordx4 v[158:159], v[32:35], off offset:576
	s_waitcnt vmcnt(19)
	s_mov_b32 s98, 0x10000
	v_lshl_add_u64 v[158:159], v[158:159], 0, s[98:99]
	v_pk_add_f32 v[30:31], v[30:31], v[212:213]
	v_pk_add_f32 v[28:29], v[28:29], v[210:211]
	global_store_dwordx4 v[158:159], v[28:31], off
	s_waitcnt vmcnt(18)
	v_pk_add_f32 v[26:27], v[26:27], v[216:217]
	v_pk_add_f32 v[24:25], v[24:25], v[214:215]
	global_store_dwordx4 v[158:159], v[24:27], off offset:64
	s_waitcnt vmcnt(17)
	v_pk_add_f32 v[22:23], v[22:23], v[168:169]
	v_pk_add_f32 v[20:21], v[20:21], v[166:167]
	global_store_dwordx4 v[158:159], v[20:23], off offset:512
	s_waitcnt vmcnt(16)
	v_pk_add_f32 v[18:19], v[18:19], v[172:173]
	v_pk_add_f32 v[16:17], v[16:17], v[170:171]
	global_store_dwordx4 v[158:159], v[16:19], off offset:576
	s_waitcnt vmcnt(15)
	s_mov_b32 s98, 0x10000
	v_lshl_add_u64 v[158:159], v[158:159], 0, s[98:99]
	v_pk_add_f32 v[14:15], v[14:15], v[176:177]
	v_pk_add_f32 v[12:13], v[12:13], v[174:175]
	global_store_dwordx4 v[158:159], v[12:15], off
	s_waitcnt vmcnt(14)
	v_pk_add_f32 v[10:11], v[10:11], v[180:181]
	v_pk_add_f32 v[8:9], v[8:9], v[178:179]
	global_store_dwordx4 v[158:159], v[8:11], off offset:64
	s_waitcnt vmcnt(13)
	v_pk_add_f32 v[6:7], v[6:7], v[184:185]
	v_pk_add_f32 v[4:5], v[4:5], v[182:183]
	global_store_dwordx4 v[158:159], v[4:7], off offset:512
	s_waitcnt vmcnt(12)
	v_pk_add_f32 v[2:3], v[2:3], v[188:189]
	v_pk_add_f32 v[0:1], v[0:1], v[186:187]
	global_store_dwordx4 v[158:159], v[0:3], off offset:576
	s_mov_b64 s[34:35], -1
	s_andn2_b64 vcc, exec, s[4:5]
	s_cbranch_vccnz .LBB0_1550
	s_andn2_b64 vcc, exec, s[6:7]
	s_cbranch_vccnz .LBB0_1549
	s_barrier
	s_branch .LBB0_1549

.LBB0_1740:
	v_lshl_add_u32 v148, s64, 8, v150
	v_lshl_or_b32 v144, s65, 8, v154
	v_ashrrev_i32_e32 v149, 31, v148
	v_ashrrev_i32_e32 v145, 31, v144
	v_lshlrev_b64 v[146:147], 12, v[148:149]
	v_lshl_add_u64 v[158:159], s[14:15], 0, v[146:147]
	v_lshlrev_b64 v[146:147], 2, v[144:145]
	v_lshl_add_u64 v[144:145], v[158:159], 0, v[146:147]
	v_mov_b32_e32 v158, v144
	v_mov_b32_e32 v159, v145
	s_mov_b32 s99, 0
	global_load_dwordx4 v[166:169], v[144:145], off
	global_load_dwordx4 v[170:173], v[144:145], off offset:64
	global_load_dwordx4 v[174:177], v[144:145], off offset:512
	global_load_dwordx4 v[178:181], v[144:145], off offset:576
	s_mov_b32 s98, 0x10000
	v_lshl_add_u64 v[144:145], v[144:145], 0, s[98:99]
	global_load_dwordx4 v[182:185], v[144:145], off
	global_load_dwordx4 v[186:189], v[144:145], off offset:64
	global_load_dwordx4 v[190:193], v[144:145], off offset:512
	global_load_dwordx4 v[194:197], v[144:145], off offset:576
	s_mov_b32 s98, 0x10000
	v_lshl_add_u64 v[144:145], v[144:145], 0, s[98:99]
	global_load_dwordx4 v[198:201], v[144:145], off
	global_load_dwordx4 v[202:205], v[144:145], off offset:64
	global_load_dwordx4 v[206:209], v[144:145], off offset:512
	global_load_dwordx4 v[210:213], v[144:145], off offset:576
	s_mov_b32 s98, 0x10000
	v_lshl_add_u64 v[144:145], v[144:145], 0, s[98:99]
	global_load_dwordx4 v[214:217], v[144:145], off
	s_waitcnt vmcnt(12)
	v_pk_add_f32 v[126:127], v[126:127], v[168:169]
	v_pk_add_f32 v[124:125], v[124:125], v[166:167]
	global_store_dwordx4 v[158:159], v[124:127], off
	global_load_dwordx4 v[166:169], v[144:145], off offset:64
	s_waitcnt vmcnt(13)
	v_pk_add_f32 v[122:123], v[122:123], v[172:173]
	v_pk_add_f32 v[120:121], v[120:121], v[170:171]
	global_store_dwordx4 v[158:159], v[120:123], off offset:64
	global_load_dwordx4 v[170:173], v[144:145], off offset:512
	s_waitcnt vmcnt(14)
	v_pk_add_f32 v[118:119], v[118:119], v[176:177]
	v_pk_add_f32 v[116:117], v[116:117], v[174:175]
	global_store_dwordx4 v[158:159], v[116:119], off offset:512
	global_load_dwordx4 v[174:177], v[144:145], off offset:576
	s_waitcnt vmcnt(15)
	v_pk_add_f32 v[110:111], v[110:111], v[180:181]
	v_pk_add_f32 v[108:109], v[108:109], v[178:179]
	global_store_dwordx4 v[158:159], v[108:111], off offset:576
	s_mov_b32 s98, 0x50000
	v_lshl_add_u64 v[144:145], v[144:145], 0, s[98:99]
	global_load_dwordx4 v[178:181], v[144:145], off
	s_waitcnt vmcnt(16)
	s_mov_b32 s98, 0x10000
	v_lshl_add_u64 v[158:159], v[158:159], 0, s[98:99]
	v_pk_add_f32 v[114:115], v[114:115], v[184:185]
	v_pk_add_f32 v[112:113], v[112:113], v[182:183]
	global_store_dwordx4 v[158:159], v[112:115], off
	global_load_dwordx4 v[182:185], v[144:145], off offset:64
	s_waitcnt vmcnt(17)
	v_pk_add_f32 v[106:107], v[106:107], v[188:189]
	v_pk_add_f32 v[104:105], v[104:105], v[186:187]
	global_store_dwordx4 v[158:159], v[104:107], off offset:64
	global_load_dwordx4 v[186:189], v[144:145], off offset:512
	s_waitcnt vmcnt(18)
	v_pk_add_f32 v[102:103], v[102:103], v[192:193]
	v_pk_add_f32 v[100:101], v[100:101], v[190:191]
	global_store_dwordx4 v[158:159], v[100:103], off offset:512
	global_load_dwordx4 v[190:193], v[144:145], off offset:576
	s_waitcnt vmcnt(19)
	v_pk_add_f32 v[98:99], v[98:99], v[196:197]
	v_pk_add_f32 v[96:97], v[96:97], v[194:195]
	global_store_dwordx4 v[158:159], v[96:99], off offset:576
	s_mov_b32 s98, 0x10000
	v_lshl_add_u64 v[144:145], v[144:145], 0, s[98:99]
	global_load_dwordx4 v[194:197], v[144:145], off
	s_waitcnt vmcnt(20)
	s_mov_b32 s98, 0x10000
	v_lshl_add_u64 v[158:159], v[158:159], 0, s[98:99]
	v_pk_add_f32 v[94:95], v[94:95], v[200:201]
	v_pk_add_f32 v[92:93], v[92:93], v[198:199]
	global_store_dwordx4 v[158:159], v[92:95], off
	global_load_dwordx4 v[198:201], v[144:145], off offset:64
	s_waitcnt vmcnt(21)
	v_pk_add_f32 v[90:91], v[90:91], v[204:205]
	v_pk_add_f32 v[88:89], v[88:89], v[202:203]
	global_store_dwordx4 v[158:159], v[88:91], off offset:64
	global_load_dwordx4 v[202:205], v[144:145], off offset:512
	s_waitcnt vmcnt(22)
	v_pk_add_f32 v[86:87], v[86:87], v[208:209]
	v_pk_add_f32 v[84:85], v[84:85], v[206:207]
	global_store_dwordx4 v[158:159], v[84:87], off offset:512
	global_load_dwordx4 v[206:209], v[144:145], off offset:576
	s_waitcnt vmcnt(23)
	v_pk_add_f32 v[82:83], v[82:83], v[212:213]
	v_pk_add_f32 v[80:81], v[80:81], v[210:211]
	global_store_dwordx4 v[158:159], v[80:83], off offset:576
	s_mov_b32 s98, 0x10000
	v_lshl_add_u64 v[144:145], v[144:145], 0, s[98:99]
	global_load_dwordx4 v[210:213], v[144:145], off
	s_waitcnt vmcnt(24)
	s_mov_b32 s98, 0x10000
	v_lshl_add_u64 v[158:159], v[158:159], 0, s[98:99]
	v_pk_add_f32 v[78:79], v[78:79], v[216:217]
	v_pk_add_f32 v[76:77], v[76:77], v[214:215]
	global_store_dwordx4 v[158:159], v[76:79], off
	global_load_dwordx4 v[214:217], v[144:145], off offset:64
	s_waitcnt vmcnt(24)
	v_pk_add_f32 v[74:75], v[74:75], v[168:169]
	v_pk_add_f32 v[72:73], v[72:73], v[166:167]
	global_store_dwordx4 v[158:159], v[72:75], off offset:64
	global_load_dwordx4 v[166:169], v[144:145], off offset:512
	s_waitcnt vmcnt(24)
	v_pk_add_f32 v[70:71], v[70:71], v[172:173]
	v_pk_add_f32 v[68:69], v[68:69], v[170:171]
	global_store_dwordx4 v[158:159], v[68:71], off offset:512
	global_load_dwordx4 v[170:173], v[144:145], off offset:576
	s_waitcnt vmcnt(24)
	v_pk_add_f32 v[66:67], v[66:67], v[176:177]
	v_pk_add_f32 v[64:65], v[64:65], v[174:175]
	global_store_dwordx4 v[158:159], v[64:67], off offset:576
	s_mov_b32 s98, 0x10000
	v_lshl_add_u64 v[144:145], v[144:145], 0, s[98:99]
	global_load_dwordx4 v[174:177], v[144:145], off
	s_waitcnt vmcnt(24)
	s_mov_b32 s98, 0x50000
	v_lshl_add_u64 v[158:159], v[158:159], 0, s[98:99]
	v_pk_add_f32 v[62:63], v[62:63], v[180:181]
	v_pk_add_f32 v[60:61], v[60:61], v[178:179]
	global_store_dwordx4 v[158:159], v[60:63], off
	global_load_dwordx4 v[178:181], v[144:145], off offset:64
	s_waitcnt vmcnt(24)
	v_pk_add_f32 v[58:59], v[58:59], v[184:185]
	v_pk_add_f32 v[56:57], v[56:57], v[182:183]
	global_store_dwordx4 v[158:159], v[56:59], off offset:64
	global_load_dwordx4 v[182:185], v[144:145], off offset:512
	s_waitcnt vmcnt(24)
	v_pk_add_f32 v[54:55], v[54:55], v[188:189]
	v_pk_add_f32 v[52:53], v[52:53], v[186:187]
	global_store_dwordx4 v[158:159], v[52:55], off offset:512
	global_load_dwordx4 v[186:189], v[144:145], off offset:576
	s_waitcnt vmcnt(24)
	v_pk_add_f32 v[50:51], v[50:51], v[192:193]
	v_pk_add_f32 v[48:49], v[48:49], v[190:191]
	global_store_dwordx4 v[158:159], v[48:51], off offset:576
	s_waitcnt vmcnt(23)
	s_mov_b32 s98, 0x10000
	v_lshl_add_u64 v[158:159], v[158:159], 0, s[98:99]
	v_pk_add_f32 v[46:47], v[46:47], v[196:197]
	v_pk_add_f32 v[44:45], v[44:45], v[194:195]
	global_store_dwordx4 v[158:159], v[44:47], off
	s_waitcnt vmcnt(22)
	v_pk_add_f32 v[42:43], v[42:43], v[200:201]
	v_pk_add_f32 v[40:41], v[40:41], v[198:199]
	global_store_dwordx4 v[158:159], v[40:43], off offset:64
	s_waitcnt vmcnt(21)
	v_pk_add_f32 v[38:39], v[38:39], v[204:205]
	v_pk_add_f32 v[36:37], v[36:37], v[202:203]
	global_store_dwordx4 v[158:159], v[36:39], off offset:512
	s_waitcnt vmcnt(20)
	v_pk_add_f32 v[34:35], v[34:35], v[208:209]
	v_pk_add_f32 v[32:33], v[32:33], v[206:207]
	global_store_dwordx4 v[158:159], v[32:35], off offset:576
	s_waitcnt vmcnt(19)
	s_mov_b32 s98, 0x10000
	v_lshl_add_u64 v[158:159], v[158:159], 0, s[98:99]
	v_pk_add_f32 v[30:31], v[30:31], v[212:213]
	v_pk_add_f32 v[28:29], v[28:29], v[210:211]
	global_store_dwordx4 v[158:159], v[28:31], off
	s_waitcnt vmcnt(18)
	v_pk_add_f32 v[26:27], v[26:27], v[216:217]
	v_pk_add_f32 v[24:25], v[24:25], v[214:215]
	global_store_dwordx4 v[158:159], v[24:27], off offset:64
	s_waitcnt vmcnt(17)
	v_pk_add_f32 v[22:23], v[22:23], v[168:169]
	v_pk_add_f32 v[20:21], v[20:21], v[166:167]
	global_store_dwordx4 v[158:159], v[20:23], off offset:512
	s_waitcnt vmcnt(16)
	v_pk_add_f32 v[18:19], v[18:19], v[172:173]
	v_pk_add_f32 v[16:17], v[16:17], v[170:171]
	global_store_dwordx4 v[158:159], v[16:19], off offset:576
	s_waitcnt vmcnt(15)
	s_mov_b32 s98, 0x10000
	v_lshl_add_u64 v[158:159], v[158:159], 0, s[98:99]
	v_pk_add_f32 v[14:15], v[14:15], v[176:177]
	v_pk_add_f32 v[12:13], v[12:13], v[174:175]
	global_store_dwordx4 v[158:159], v[12:15], off
	s_waitcnt vmcnt(14)
	v_pk_add_f32 v[10:11], v[10:11], v[180:181]
	v_pk_add_f32 v[8:9], v[8:9], v[178:179]
	global_store_dwordx4 v[158:159], v[8:11], off offset:64
	s_waitcnt vmcnt(13)
	v_pk_add_f32 v[6:7], v[6:7], v[184:185]
	v_pk_add_f32 v[4:5], v[4:5], v[182:183]
	global_store_dwordx4 v[158:159], v[4:7], off offset:512
	s_waitcnt vmcnt(12)
	v_pk_add_f32 v[2:3], v[2:3], v[188:189]
	v_pk_add_f32 v[0:1], v[0:1], v[186:187]
	global_store_dwordx4 v[158:159], v[0:3], off offset:576
	s_mov_b64 s[28:29], -1
	s_and_b64 vcc, exec, s[4:5]
	s_cbranch_vccnz .LBB0_1725
	s_andn2_b64 vcc, exec, s[10:11]
	s_cbranch_vccnz .LBB0_1724
	s_barrier
	s_branch .LBB0_1724

	.amdhsa_kernel _Z9hymba_fwd6Params
		.amdhsa_group_segment_fixed_size 0
		.amdhsa_private_segment_fixed_size 0
		.amdhsa_kernarg_size 488
		.amdhsa_user_sgpr_count 2
		.amdhsa_user_sgpr_dispatch_ptr 0
		.amdhsa_user_sgpr_queue_ptr 0
		.amdhsa_user_sgpr_kernarg_segment_ptr 1
		.amdhsa_user_sgpr_dispatch_id 0
		.amdhsa_user_sgpr_kernarg_preload_length 0
		.amdhsa_user_sgpr_kernarg_preload_offset 0
		.amdhsa_user_sgpr_private_segment_size 0
		.amdhsa_uses_dynamic_stack 0
		.amdhsa_enable_private_segment 0
		.amdhsa_system_sgpr_workgroup_id_x 1
		.amdhsa_system_sgpr_workgroup_id_y 0
		.amdhsa_system_sgpr_workgroup_id_z 0
		.amdhsa_system_sgpr_workgroup_info 0
		.amdhsa_system_vgpr_workitem_id 2
		.amdhsa_next_free_vgpr 233
		.amdhsa_next_free_sgpr 100
		.amdhsa_accum_offset 236
		.amdhsa_reserve_vcc 1
		.amdhsa_float_round_mode_32 0
		.amdhsa_float_round_mode_16_64 0
		.amdhsa_float_denorm_mode_32 3
		.amdhsa_float_denorm_mode_16_64 3
		.amdhsa_dx10_clamp 1
		.amdhsa_ieee_mode 1
		.amdhsa_fp16_overflow 0
		.amdhsa_tg_split 0
		.amdhsa_exception_fp_ieee_invalid_op 0
		.amdhsa_exception_fp_denorm_src 0
		.amdhsa_exception_fp_ieee_div_zero 0
		.amdhsa_exception_fp_ieee_overflow 0
		.amdhsa_exception_fp_ieee_underflow 0
		.amdhsa_exception_fp_ieee_inexact 0
		.amdhsa_exception_int_div_zero 0
	.end_amdhsa_kernel

amdhsa.kernels:
  - .agpr_count:     0
    .args:
      - .offset:         0
        .size:           232
        .value_kind:     by_value
      - .offset:         232
        .size:           4
        .value_kind:     hidden_block_count_x
      - .offset:         236
        .size:           4
        .value_kind:     hidden_block_count_y
      - .offset:         240
        .size:           4
        .value_kind:     hidden_block_count_z
      - .offset:         244
        .size:           2
        .value_kind:     hidden_group_size_x
      - .offset:         246
        .size:           2
        .value_kind:     hidden_group_size_y
      - .offset:         248
        .size:           2
        .value_kind:     hidden_group_size_z
      - .offset:         250
        .size:           2
        .value_kind:     hidden_remainder_x
      - .offset:         252
        .size:           2
        .value_kind:     hidden_remainder_y
      - .offset:         254
        .size:           2
        .value_kind:     hidden_remainder_z
      - .offset:         272
        .size:           8
        .value_kind:     hidden_global_offset_x
      - .offset:         280
        .size:           8
        .value_kind:     hidden_global_offset_y
      - .offset:         288
        .size:           8
        .value_kind:     hidden_global_offset_z
      - .offset:         296
        .size:           2
        .value_kind:     hidden_grid_dims
      - .offset:         320
        .size:           8
        .value_kind:     hidden_multigrid_sync_arg
      - .offset:         352
        .size:           4
        .value_kind:     hidden_dynamic_lds_size
    .group_segment_fixed_size: 0
    .kernarg_segment_align: 8
    .kernarg_segment_size: 488
    .language:       OpenCL C
    .language_version:
      - 2
      - 0
    .max_flat_workgroup_size: 512
    .name:           _Z9hymba_fwd6Params
    .private_segment_fixed_size: 0
    .sgpr_count:     106
    .sgpr_spill_count: 4
    .symbol:         _Z9hymba_fwd6Params.kd
    .uniform_work_group_size: 1
    .uses_dynamic_stack: false
    .vgpr_count:     233
    .vgpr_spill_count: 0
    .wavefront_size: 64
